# static s_setprio 1 for waves 4-7 across the P4 unit loop (priority-raise lever), reset before pool GEMM
# speedup vs baseline: 1.0010x; 1.0004x over previous
.LBB0_405:
	s_or_b64 exec, exec, s[0:1]
	s_add_i32 s86, 0, 0x27090
	s_cmp_lg_u32 s86, -1
	s_cselect_b32 s0, s86, 0
	s_cselect_b32 s1, s5, 0
	v_mov_b32_e32 v2, s0
	v_mov_b32_e32 v3, s1
	s_waitcnt lgkmcnt(0)
	s_barrier
	flat_load_dword v1, v[2:3] sc0 sc1
	s_waitcnt vmcnt(0) lgkmcnt(0)
	v_readfirstlane_b32 s36, v1
	s_cmpk_gt_i32 s36, 0x803
	s_cbranch_scc1 .LBB0_799
	s_add_u32 s50, s18, 0x6300000
	s_addc_u32 s51, s19, 0
	s_add_u32 s0, s18, 0xe700000
	s_addc_u32 s1, s19, 0
	v_writelane_b32 v250, s0, 44
	v_ashrrev_i32_e32 v1, 6, v0
	v_and_b32_e32 v185, 3, v1
	v_writelane_b32 v250, s1, 45
	s_add_u32 s0, s18, 0xeb20000
	s_addc_u32 s1, s19, 0
	v_writelane_b32 v250, s0, 46
	v_lshlrev_b32_e32 v2, 10, v185
	v_and_b32_e32 v184, 63, v0
	v_writelane_b32 v250, s1, 47
	s_add_u32 s0, s18, 0x10d28000
	s_addc_u32 s1, s19, 0
	v_writelane_b32 v250, s0, 48
	v_lshlrev_b32_e32 v3, 3, v0
	v_and_b32_e32 v192, 0xffffffc0, v0
	v_writelane_b32 v250, s1, 49
	s_add_u32 s0, s18, 0x14f28000
	s_addc_u32 s1, s19, 0
	v_writelane_b32 v250, s0, 50
	s_add_i32 s17, 0, 0x23000
	v_lshlrev_b32_e32 v190, 3, v1
	v_writelane_b32 v250, s1, 51
	v_cmp_gt_u32_e64 s[0:1], 64, v0
	v_lshl_add_u32 v191, v1, 12, s17
	v_and_b32_e32 v3, 0xfffff800, v3
	v_writelane_b32 v250, s0, 36
	v_lshl_add_u32 v187, v185, 12, s17
	v_readlane_b32 s6, v251, 52
	v_writelane_b32 v250, s1, 37
	s_movk_i32 s1, 0x100
	v_readlane_b32 s0, v250, 20
	v_cmp_gt_u32_e64 s[40:41], s1, v0
	v_and_b32_e32 v0, 0xffffff00, v0
	v_add_u32_e32 v186, s0, v2
	s_mov_b32 s0, 0x8400
	v_mad_u32_u24 v189, v185, s0, 0
	s_movk_i32 s0, 0x4400
	v_mul_lo_u32 v1, v1, s0
	v_cmp_eq_u32_e64 s[0:1], s1, v0
	v_add_u32_e32 v193, 0, v1
	v_readlane_b32 s10, v251, 55
	v_writelane_b32 v250, s0, 52
	v_readlane_b32 s12, v251, 57
	v_add_u32_e32 v188, v187, v3
	v_writelane_b32 v250, s1, 53
	s_add_u32 s0, s18, 0x6300004
	v_writelane_b32 v250, s0, 54
	s_addc_u32 s0, s19, 0
	v_writelane_b32 v250, s0, 55
	s_add_u32 s0, s18, 0x6300008
	v_writelane_b32 v250, s0, 56
	s_addc_u32 s0, s19, 0
	v_writelane_b32 v250, s0, 57
	s_add_u32 s0, s18, 0x630000c
	v_writelane_b32 v250, s0, 58
	s_addc_u32 s0, s19, 0
	v_writelane_b32 v250, s0, 59
	v_add_u32_e32 v194, 0x11000, v193
	v_readlane_b32 s0, v250, 21
	v_readlane_b32 s7, v251, 53
	v_readlane_b32 s4, v251, 54
	v_add_u32_e32 v195, s0, v2
	v_readlane_b32 s11, v251, 56
	v_readlane_b32 s13, v251, 58
	v_readlane_b32 s14, v250, 2
	s_cmp_lg_u64 s[40:41], 0
	s_cbranch_scc1 .Lp4prio_skip
	s_setprio 1
.Lp4prio_skip:
	s_branch .LBB0_408

.LBB0_799:
	s_setprio 0
	s_add_u32 s0, s18, 0xfca8000
	s_addc_u32 s1, s19, 0
	v_readlane_b32 s4, v250, 30
	s_add_u32 s36, s18, 0x24128000
	v_readlane_b32 s5, v250, 31
	s_addc_u32 s37, s19, 0
	s_lshl_b64 s[38:39], s[4:5], 12
	s_mov_b64 s[40:41], s[18:19]
	v_readlane_b32 s4, v252, 19
	v_readlane_b32 s8, v252, 23
	v_readlane_b32 s9, v252, 24
	s_add_u32 s38, s8, s38
	v_readlane_b32 s10, v252, 25
	v_readlane_b32 s11, v252, 26
	s_addc_u32 s39, s9, s39
	v_readlane_b32 s4, v250, 29
	s_mov_b64 s[10:11], s[40:41]
	s_cmpk_gt_i32 s4, 0x7f
	v_readlane_b32 s5, v252, 20
	v_readlane_b32 s6, v252, 21
	v_readlane_b32 s7, v252, 22
	v_readlane_b32 s12, v252, 27
	v_readlane_b32 s13, v252, 28
	v_readlane_b32 s14, v252, 29
	v_readlane_b32 s15, v252, 30
	v_readlane_b32 s16, v252, 31
	v_readlane_b32 s17, v252, 32
	v_readlane_b32 s18, v252, 33
	v_readlane_b32 s19, v252, 34
	s_cbranch_scc1 .LBB0_806
	s_add_u32 s48, s10, 0xec28000
	v_readlane_b32 s58, v250, 29
	s_addc_u32 s49, s11, 0
	s_lshl_b32 s40, s58, 8
	v_readlane_b32 s4, v250, 32
	s_or_b32 s50, s40, 0xb0
	s_lshl_b32 s51, s4, 8
	s_branch .LBB0_802
